# P5 role split: workgroups >=128 run the w_up/w_down transposes before the out-proj GEMM, the rest after, so HBM-bound and MFMA-bound work overlap chip-wide
# speedup vs baseline: 1.0041x; 1.0029x over previous
;     __device__ bool next(int i, Unit& u) const { if (i >= 2) return false; const int x = c & 7, j = c >> 3; u.pm = 8 * x + (j >> 3) + 4 * i; u.pn = j & 7; return true; }
; #define IDS() int tid = threadIdx.x; asm volatile("" : "+v"(tid)); const int lane = tid & 63, wave = __builtin_amdgcn_readfirstlane(tid >> 6); const int gtid = blockIdx.x * NTHR + tid, gw = blockIdx.x * (NTHR / 64) + wave; LAS float* scr = (LAS float*)(lds + wave * 16384); (void)lane; (void)gtid; (void)gw; (void)scr;
;     __device__ bool next(int i, Unit& u) const {
;         const long L = (long)i * G + c; if (L >= nwg) return false;
;         int wgid = (int)L; { const int q = nwg / NXCD, r = nwg % NXCD, xcd = wgid % NXCD, off = wgid / NXCD; wgid = (xcd < r ? xcd * (q + 1) : r * (q + 1) + (xcd - r) * q) + off; }
;         const int nig = WGM * nN, gid = wgid / nig, fm = gid * WGM, gsz = (nM - fm) < WGM ? (nM - fm) : WGM;
;         u.pm = fm + ((wgid % nig) % gsz); u.pn = (wgid % nig) / gsz; return true;
; __global__ void __launch_bounds__(NTHR, 2) hybrid_block_fwd(Args a) {
;     ...
;     { IDS();
;         { pg8::Gemm g{MERGED, WT_OUT, D, D, 0}; pg8::StaticOrder S; S.init(M, D, NWG, (int)blockIdx.x);
;           EpiResid1 E{XB, RSTD1, X1B, SS2}; pg8::gemm_phase(lds, g, S, E); }
.LBB0_814:
	s_or_b64 exec, exec, s[0:1]
	v_mov_b32_e32 v155, v212
	v_mov_b32_e32 v8, v212
	s_waitcnt lgkmcnt(0)
	s_barrier
	v_readlane_b32 s99, v248, 8
	s_mov_b32 s98, 0
	s_nop 3
	s_bitcmp1_b32 s99, 16
	s_cbranch_scc0 .Lp5_gemm_start
	s_mov_b32 s98, 1
	s_mov_b64 s[96:97], s[6:7]
	s_mov_b64 s[100:101], s[8:9]
	s_mov_b32 s99, s28
	v_readfirstlane_b32 s14, v155
	s_branch .LBB0_852
.Lp5_gemm_start:
	s_and_b64 vcc, exec, s[8:9]
	v_readfirstlane_b32 s14, v155
	v_readfirstlane_b32 s0, v8
	s_cbranch_vccz .LBB0_816
	s_lshl_b32 s1, s30, 6
	s_and_b64 s[4:5], s[6:7], exec
	s_cselect_b32 s1, s18, s1
	s_add_i32 s1, s1, s29
	s_ashr_i32 s4, s1, 31
	s_lshr_b32 s4, s4, 28
	s_add_i32 s4, s1, s4
	s_ashr_i32 s5, s4, 4
	s_and_b32 s4, s4, 0xfff0
	s_sub_i32 s1, s1, s4
	s_bfe_u32 s4, s1, 0x10007
	s_add_i32 s4, s1, s4
	s_bfe_i32 s6, s4, 0x80000
	s_and_b32 s4, s4, 0xfe
	s_sub_i32 s1, s1, s4
	s_lshl_b32 s5, s5, 1
	s_sext_i32_i16 s6, s6
	s_sext_i32_i8 s1, s1
	s_add_i32 s58, s5, s1
	s_ashr_i32 s56, s6, 1

; #define LAS __attribute__((address_space(3)))
; #define LDS_WAIT() asm volatile("s_waitcnt lgkmcnt(0)" ::: "memory")
; __device__ __forceinline__ void tr_tile(const float* src, int ldw, const float* ksc, bf16_t* dst, int ldd, LAS float* scr, int lane) {
;     float v[32];
; #pragma unroll
;     for (int i = 0; i < 32; ++i) v[i] = src[(size_t)(2 * i + (lane >> 5)) * ldw + (lane & 31)];
; #pragma unroll
;     for (int i = 0; i < 32; ++i) scr[(2 * i + (lane >> 5)) * 33 + (lane & 31)] = v[i];
;     LDS_WAIT();
;     const int c = lane & 7;
;     f32x4 k0 = (f32x4){1.f, 1.f, 1.f, 1.f}, k1 = k0;
;     if (ksc) { k0 = *(const f32x4*)(ksc + 8 * c); k1 = *(const f32x4*)(ksc + 8 * c + 4); }
; #pragma unroll
;     for (int j = 0; j < 4; ++j) { const int n = (lane >> 3) + 8 * j; const LAS float* s = scr + (8 * c) * 33 + n;
; __global__ void __launch_bounds__(NTHR, 2) hybrid_block_fwd(Args a) {
;     ...
;         constexpr int I_UP = (D / 64) * (2 * FF / 32), I_DOWN = (FF / 64) * (D / 32);
;         for (int rep2_ = 0; rep2_ < 1 + ((REP_MASK >> 12) & 1); ++rep2_)
;         for (int it = gw; it < I_UP + I_DOWN; it += NWV) {
;             if (it < I_UP) {
;                 const int nblk = 2 * FF / 32, kb = it / nblk, nb = it % nblk, n0 = nb * 32, pn = n0 >> 8, bj = (n0 >> 7) & 1, j0 = n0 & 127, k0 = kb * 64;
;                 tr_tile(w_up + (size_t)k0 * (2 * FF) + bj * FF + pn * 128 + j0, 2 * FF, g_mlp + k0, WT_UP + (size_t)n0 * D + k0, D, scr, lane);
;             } else tr_plain(w_down, FF, D, nullptr, WT_DOWN, it - I_UP, scr, lane);
;         }
.LBB0_852:
	s_cmp_eq_u32 s98, 2
	s_cbranch_scc1 .Lp5_tr_done
	s_ashr_i32 s0, s14, 6
	v_readlane_b32 s1, v248, 36
	s_add_i32 s8, s0, s1
	s_add_u32 s27, s94, 0x10f00000
	s_addc_u32 s28, s95, 0
	s_cmpk_gt_i32 s8, 0x47ff
	s_cbranch_scc1 .LBB0_862
	s_waitcnt lgkmcnt(0)
	v_bfe_u32 v1, v155, 5, 1
	s_movk_i32 s1, 0x84
	v_mov_b32_e32 v8, 0x630
	v_mad_u32_u24 v15, v1, s1, v8
	v_mov_b32_e32 v8, 0xc60
	s_lshl_b32 s0, s0, 14
	v_and_b32_e32 v3, 31, v155
	v_mad_u32_u24 v17, v1, s1, v8
	v_and_b32_e32 v8, 7, v155
	v_bfe_u32 v19, v155, 3, 3
	s_add_i32 s0, s0, 0
	v_lshl_or_b32 v0, v1, 11, v3
	v_mov_b32_e32 v9, 0
	v_mul_u32_u24_e32 v7, 0x84, v1
	v_lshlrev_b32_e32 v10, 3, v8
	v_mul_u32_u24_e32 v11, 0x420, v8
	v_lshlrev_b32_e32 v12, 2, v19
	v_mul_u32_u24_e32 v1, 0x3000, v1
	v_lshlrev_b32_e32 v8, 5, v8
	v_add3_u32 v11, s0, v11, v12
	v_or_b32_e32 v82, v1, v3
	v_lshl_add_u64 v[12:13], s[80:81], 0, v[8:9]
	v_lshlrev_b32_e32 v8, 11, v19
	v_or_b32_e32 v2, 0x1000, v0
	v_or_b32_e32 v4, 0x2000, v0
	v_or_b32_e32 v6, 0x3000, v0
	v_or_b32_e32 v14, 0x4000, v0
	v_or_b32_e32 v16, 0x5000, v0
	v_or_b32_e32 v18, 0x6000, v0
	v_or_b32_e32 v20, 0x7000, v0
	v_or_b32_e32 v22, 0x8000, v0
	v_or_b32_e32 v34, 0x9000, v0
	v_or_b32_e32 v36, 0xa000, v0
	v_or_b32_e32 v38, 0xb000, v0
	v_or_b32_e32 v40, 0xc000, v0
	v_or_b32_e32 v42, 0xd000, v0
	v_or_b32_e32 v44, 0xe000, v0
	v_or_b32_e32 v46, 0xf000, v0
	v_or_b32_e32 v48, 0x10000, v0
	v_or_b32_e32 v50, 0x11000, v0
	v_or_b32_e32 v52, 0x12000, v0
	v_or_b32_e32 v54, 0x13000, v0
	v_or_b32_e32 v56, 0x14000, v0
	v_or_b32_e32 v58, 0x15000, v0
	v_or_b32_e32 v60, 0x16000, v0
	v_or_b32_e32 v62, 0x17000, v0
	v_or_b32_e32 v64, 0x18000, v0
	v_or_b32_e32 v66, 0x19000, v0
	v_or_b32_e32 v68, 0x1a000, v0
	v_or_b32_e32 v70, 0x1b000, v0
	v_or_b32_e32 v72, 0x1c000, v0
	v_or_b32_e32 v74, 0x1d000, v0
	v_or_b32_e32 v76, 0x1e000, v0
	v_or_b32_e32 v78, 0x1f000, v0
	v_lshl_add_u32 v5, v3, 2, s0
	v_mul_u32_u24_e32 v80, 0x1800, v19
	v_add_u32_e32 v84, 0x6000, v82
	v_add_u32_e32 v86, 0xc000, v82
	v_add_u32_e32 v88, 0x12000, v82
	v_or_b32_e32 v90, 0x18000, v82
	v_add_u32_e32 v92, 0x1e000, v82
	v_add_u32_e32 v94, 0x24000, v82
	v_add_u32_e32 v96, 0x2a000, v82
	v_or_b32_e32 v98, 0x30000, v82
	v_add_u32_e32 v100, 0x36000, v82
	v_add_u32_e32 v102, 0x3c000, v82
	v_add_u32_e32 v104, 0x42000, v82
	v_or_b32_e32 v106, 0x48000, v82
	v_add_u32_e32 v108, 0x4e000, v82
	v_add_u32_e32 v110, 0x54000, v82
	v_add_u32_e32 v112, 0x5a000, v82
	v_or_b32_e32 v114, 0x60000, v82
	v_add_u32_e32 v116, 0x66000, v82
	v_add_u32_e32 v118, 0x6c000, v82
	v_add_u32_e32 v120, 0x72000, v82
	v_or_b32_e32 v122, 0x78000, v82
	v_add_u32_e32 v124, 0x7e000, v82
	v_add_u32_e32 v126, 0x84000, v82
	v_add_u32_e32 v128, 0x8a000, v82
	v_or_b32_e32 v130, 0x90000, v82
	v_add_u32_e32 v132, 0x96000, v82
	v_add_u32_e32 v134, 0x9c000, v82
	v_add_u32_e32 v136, 0xa2000, v82
	v_or_b32_e32 v138, 0xa8000, v82
	v_add_u32_e32 v140, 0xae000, v82
	v_add_u32_e32 v142, 0xb4000, v82
	v_add_u32_e32 v144, 0xba000, v82
	v_or_b32_e32 v146, 0x4000, v8
	v_or_b32_e32 v148, 0x8000, v8
	v_or_b32_e32 v150, 0xc000, v8
	s_cmp_lg_u64 s[80:81], 0
	s_mov_b32 s9, 0x18000
	s_mov_b32 s10, 0x30000
	s_cselect_b64 s[0:1], -1, 0
	s_lshl_b32 s11, s8, 5
	s_lshl_b32 s12, s8, 4
	v_lshlrev_b32_e32 v24, 2, v0
	v_lshlrev_b32_e32 v25, 2, v2
	v_lshlrev_b32_e32 v26, 2, v4
	v_lshlrev_b32_e32 v27, 2, v6
	v_lshlrev_b32_e32 v28, 2, v14
	v_lshlrev_b32_e32 v29, 2, v16
	v_lshlrev_b32_e32 v30, 2, v18
	v_lshlrev_b32_e32 v31, 2, v20
	v_lshlrev_b32_e32 v32, 2, v22
	v_lshlrev_b32_e32 v33, 2, v34
	v_lshlrev_b32_e32 v34, 2, v36
	v_lshlrev_b32_e32 v35, 2, v38
	v_lshlrev_b32_e32 v36, 2, v40
	v_lshlrev_b32_e32 v37, 2, v42
	v_lshlrev_b32_e32 v38, 2, v44
	v_lshlrev_b32_e32 v39, 2, v46
	v_lshlrev_b32_e32 v40, 2, v48
	v_lshlrev_b32_e32 v41, 2, v50
	v_lshlrev_b32_e32 v42, 2, v52
	v_lshlrev_b32_e32 v43, 2, v54
	v_lshlrev_b32_e32 v44, 2, v56
	v_lshlrev_b32_e32 v45, 2, v58
	v_lshlrev_b32_e32 v46, 2, v60
	v_lshlrev_b32_e32 v47, 2, v62
	v_lshlrev_b32_e32 v48, 2, v64
	v_lshlrev_b32_e32 v49, 2, v66
	v_lshlrev_b32_e32 v50, 2, v68
	v_lshlrev_b32_e32 v51, 2, v70
	v_lshlrev_b32_e32 v52, 2, v72
	v_lshlrev_b32_e32 v53, 2, v74
	v_lshlrev_b32_e32 v54, 2, v76
	v_lshlrev_b32_e32 v55, 2, v78
	v_lshlrev_b32_e32 v14, 1, v80
	v_lshlrev_b32_e32 v56, 2, v82
	v_lshlrev_b32_e32 v57, 2, v84
	v_lshlrev_b32_e32 v58, 2, v86
	v_lshlrev_b32_e32 v59, 2, v88
	v_lshlrev_b32_e32 v60, 2, v90
	v_lshlrev_b32_e32 v61, 2, v92
	v_lshlrev_b32_e32 v62, 2, v94
	v_lshlrev_b32_e32 v63, 2, v96
	v_lshlrev_b32_e32 v64, 2, v98
	v_lshlrev_b32_e32 v65, 2, v100
	v_lshlrev_b32_e32 v66, 2, v102
	v_lshlrev_b32_e32 v67, 2, v104
	v_lshlrev_b32_e32 v68, 2, v106
	v_lshlrev_b32_e32 v69, 2, v108
	v_lshlrev_b32_e32 v70, 2, v110
	v_lshlrev_b32_e32 v71, 2, v112
	v_lshlrev_b32_e32 v72, 2, v114
	v_lshlrev_b32_e32 v73, 2, v116
	v_lshlrev_b32_e32 v74, 2, v118
	v_lshlrev_b32_e32 v75, 2, v120
	v_lshlrev_b32_e32 v76, 2, v122
	v_lshlrev_b32_e32 v77, 2, v124
	v_lshlrev_b32_e32 v78, 2, v126
	v_lshlrev_b32_e32 v79, 2, v128
	v_lshlrev_b32_e32 v80, 2, v130
	v_lshlrev_b32_e32 v81, 2, v132
	v_lshlrev_b32_e32 v82, 2, v134
	v_lshlrev_b32_e32 v83, 2, v136
	v_lshlrev_b32_e32 v84, 2, v138
	v_lshlrev_b32_e32 v85, 2, v140
	v_lshlrev_b32_e32 v86, 2, v142
	v_lshlrev_b32_e32 v87, 2, v144
	v_lshlrev_b32_e32 v16, 1, v8
	v_lshlrev_b32_e32 v18, 1, v146
	v_lshlrev_b32_e32 v20, 1, v148
	v_lshlrev_b32_e32 v22, 1, v150
	v_add_u32_e32 v88, v5, v7
	v_add_u32_e32 v89, v5, v15
	v_add_u32_e32 v90, v5, v17
	s_branch .LBB0_857

; __device__ __forceinline__ unsigned xb_ld(unsigned* p)              { return __hip_atomic_load(p, __ATOMIC_RELAXED, __HIP_MEMORY_SCOPE_AGENT); }
; __device__ __forceinline__ unsigned xb_add(unsigned* p, unsigned v) { return __hip_atomic_fetch_add(p, v, __ATOMIC_RELAXED, __HIP_MEMORY_SCOPE_AGENT); }
; __device__ __forceinline__ void xcd_barrier_complete(unsigned* bar, unsigned x, unsigned& nloc, unsigned& nx) {
;     const unsigned G = gridDim.x * gridDim.y * gridDim.z;
;     unsigned sum, cnt, mine, sp = 0u;
;     for (;;) {
;         sum = 0u; cnt = 0u; mine = 0u;
; #pragma unroll
;         for (unsigned j = 0; j < 16; ++j) { const unsigned c = xb_ld(&bar[XB_XCNT(j)]); sum += c; cnt += (c > 0u) ? 1u : 0u; mine = (j == x) ? c : mine; }
; __device__ __forceinline__ void xcd_barrier(const XcdBarrier& b) {
;     asm volatile("s_waitcnt vmcnt(0)" ::: "memory");
;     __syncthreads();
;     if (threadIdx.x == 0) {
;         unsigned* bar = b.bar;
;         __builtin_amdgcn_s_waitcnt(0);
;         unsigned nloc = b.st[0], nx = b.st[1];
;         if (nloc == 0u) { xcd_barrier_complete(bar, b.x, nloc, nx); b.st[0] = nloc; b.st[1] = nx; }
;         const unsigned old = xb_add(&bar[XB_XSUB(b.x)], 1u);
.LBB0_862:
	s_cmp_eq_u32 s98, 1
	s_cbranch_scc0 .Lp5_tr_done
	s_mov_b32 s98, 2
	s_mov_b64 s[6:7], s[96:97]
	s_mov_b64 s[8:9], s[100:101]
	s_mov_b32 s28, s99
	v_mov_b32_e32 v8, v212
	s_waitcnt lgkmcnt(0)
	s_barrier
	s_branch .Lp5_gemm_start
.Lp5_tr_done:
	s_add_u32 s27, s94, 0x10f00000
	s_addc_u32 s28, s95, 0
	s_waitcnt vmcnt(0)
	v_readlane_b32 s72, v248, 6
	v_readlane_b32 s73, v248, 7
	s_waitcnt lgkmcnt(0)
	s_barrier
	s_and_saveexec_b64 s[0:1], s[72:73]
	s_xor_b64 s[0:1], exec, s[0:1]
	s_mov_b64 s[74:75], s[2:3]
	s_cbranch_execz .LBB0_915
	s_add_i32 s4, 0, 0x20020
	v_mov_b32_e32 v0, s4
	s_waitcnt vmcnt(0) expcnt(0) lgkmcnt(0)
	ds_read_b32 v2, v0
	s_add_i32 s4, 0, 0x20024
	v_mov_b32_e32 v0, s4
	ds_read_b32 v0, v0
	s_waitcnt lgkmcnt(1)
	v_cmp_ne_u32_e32 vcc, 0, v2
	s_cbranch_vccnz .LBB0_878
	v_readlane_b32 s4, v248, 2
	v_readlane_b32 s5, v248, 3
	v_readlane_b32 s6, v248, 1
	s_mul_i32 s21, s5, s6
	s_mul_i32 s21, s21, s4
	s_add_u32 s4, s94, 0x40200
	s_addc_u32 s5, s95, 0
	s_add_u32 s6, s94, 0x40400
	s_addc_u32 s7, s95, 0
	s_add_u32 s8, s94, 0x40500
	s_addc_u32 s9, s95, 0
	s_add_u32 s10, s94, 0x40600
	s_addc_u32 s11, s95, 0
	s_add_u32 s16, s94, 0x40700
	s_addc_u32 s17, s95, 0
	s_add_u32 s18, s94, 0x40800
	s_addc_u32 s19, s95, 0
	s_add_u32 s24, s94, 0x40900
	s_addc_u32 s25, s95, 0
	s_add_u32 s38, s94, 0x40a00
	s_addc_u32 s39, s95, 0
	s_add_u32 s42, s94, 0x40b00
	s_addc_u32 s43, s95, 0
	s_add_u32 s50, s94, 0x40c00
	s_addc_u32 s51, s95, 0
	s_add_u32 s52, s94, 0x40d00
	s_addc_u32 s53, s95, 0
	s_add_u32 s54, s94, 0x40e00
	s_addc_u32 s55, s95, 0
	s_add_u32 s56, s94, 0x40f00
	s_addc_u32 s57, s95, 0
	s_add_u32 s58, s94, 0x41000
	s_addc_u32 s59, s95, 0
	s_add_u32 s60, s94, 0x41100
	s_addc_u32 s61, s95, 0
	s_add_u32 s34, s94, 0x41200
	s_addc_u32 s35, s95, 0
	s_add_u32 s48, s94, 0x41300
	s_addc_u32 s49, s95, 0
	s_mov_b32 s22, 1
	v_mov_b32_e32 v16, 0
	s_branch .LBB0_866

; __global__ void __launch_bounds__(NTHR, 2) hybrid_block_fwd(Args a) {
	.amdhsa_kernel _Z16hybrid_block_fwd4Args
		.amdhsa_group_segment_fixed_size 0
		.amdhsa_private_segment_fixed_size 0
		.amdhsa_kernarg_size 448
		.amdhsa_user_sgpr_count 2
		.amdhsa_user_sgpr_dispatch_ptr 0
		.amdhsa_user_sgpr_queue_ptr 0
		.amdhsa_user_sgpr_kernarg_segment_ptr 1
		.amdhsa_user_sgpr_dispatch_id 0
		.amdhsa_user_sgpr_kernarg_preload_length 0
		.amdhsa_user_sgpr_kernarg_preload_offset 0
		.amdhsa_user_sgpr_private_segment_size 0
		.amdhsa_uses_dynamic_stack 0
		.amdhsa_enable_private_segment 0
		.amdhsa_system_sgpr_workgroup_id_x 1
		.amdhsa_system_sgpr_workgroup_id_y 0
		.amdhsa_system_sgpr_workgroup_id_z 0
		.amdhsa_system_sgpr_workgroup_info 0
		.amdhsa_system_vgpr_workitem_id 2
		.amdhsa_next_free_vgpr 249
		.amdhsa_next_free_sgpr 102
		.amdhsa_accum_offset 252
		.amdhsa_reserve_vcc 1
		.amdhsa_float_round_mode_32 0
		.amdhsa_float_round_mode_16_64 0
		.amdhsa_float_denorm_mode_32 3
		.amdhsa_float_denorm_mode_16_64 3
		.amdhsa_dx10_clamp 1
		.amdhsa_ieee_mode 1
		.amdhsa_fp16_overflow 0
		.amdhsa_tg_split 0
		.amdhsa_exception_fp_ieee_invalid_op 0
		.amdhsa_exception_fp_denorm_src 0
		.amdhsa_exception_fp_ieee_div_zero 0
		.amdhsa_exception_fp_ieee_overflow 0
		.amdhsa_exception_fp_ieee_underflow 0
		.amdhsa_exception_fp_ieee_inexact 0
		.amdhsa_exception_int_div_zero 0
	.end_amdhsa_kernel

; __global__ void __launch_bounds__(NTHR, 2) hybrid_block_fwd(Args a) {
amdhsa.kernels:
  - .agpr_count:     0
    .args:
      - .offset:         0
        .size:           192
        .value_kind:     by_value
      - .offset:         192
        .size:           4
        .value_kind:     hidden_block_count_x
      - .offset:         196
        .size:           4
        .value_kind:     hidden_block_count_y
      - .offset:         200
        .size:           4
        .value_kind:     hidden_block_count_z
      - .offset:         204
        .size:           2
        .value_kind:     hidden_group_size_x
      - .offset:         206
        .size:           2
        .value_kind:     hidden_group_size_y
      - .offset:         208
        .size:           2
        .value_kind:     hidden_group_size_z
      - .offset:         210
        .size:           2
        .value_kind:     hidden_remainder_x
      - .offset:         212
        .size:           2
        .value_kind:     hidden_remainder_y
      - .offset:         214
        .size:           2
        .value_kind:     hidden_remainder_z
      - .offset:         232
        .size:           8
        .value_kind:     hidden_global_offset_x
      - .offset:         240
        .size:           8
        .value_kind:     hidden_global_offset_y
      - .offset:         248
        .size:           8
        .value_kind:     hidden_global_offset_z
      - .offset:         256
        .size:           2
        .value_kind:     hidden_grid_dims
      - .offset:         280
        .size:           8
        .value_kind:     hidden_multigrid_sync_arg
      - .offset:         312
        .size:           4
        .value_kind:     hidden_dynamic_lds_size
    .group_segment_fixed_size: 0
    .kernarg_segment_align: 8
    .kernarg_segment_size: 448
    .language:       OpenCL C
    .language_version:
      - 2
      - 0
    .max_flat_workgroup_size: 512
    .name:           _Z16hybrid_block_fwd4Args
    .private_segment_fixed_size: 0
    .sgpr_count:     108
    .sgpr_spill_count: 38
    .symbol:         _Z16hybrid_block_fwd4Args.kd
    .uniform_work_group_size: 1
    .uses_dynamic_stack: false
    .vgpr_count:     249
    .vgpr_spill_count: 0
    .wavefront_size: 64
